# attention: first V-fragment LDS reads of each PV section issued behind the last K-fragment reads of the QK section (latency covered by last QK MFMAs + global-load block)
# speedup vs baseline: 1.0125x; 1.0125x over previous
; __device__ __forceinline__ void finishSM(f32x16& p0, f32x16& p1, float alpha, float& l_reg, bf16x8& pa0, bf16x8& pa1, bf16x8& pa2, bf16x8& pa3) {
;     for (int r = 0; r < 16; ++r) p1[r] = __builtin_amdgcn_exp2f(p1[r]);
;     float ps = 0; for (int r = 0; r < 16; ++r) ps += p0[r]; for (int r = 0; r < 16; ++r) ps += p1[r];
;     { auto rr = __builtin_amdgcn_permlane32_swap(__float_as_uint(ps), __float_as_uint(ps), false, false);
;       ps = __uint_as_float(rr[0]) + __uint_as_float(rr[1]); }
;     l_reg = l_reg * alpha + ps;
;     ...
;     PK4(p0, 0, pa0); PK4(p0, 8, pa1); PK4(p1, 0, pa2); PK4(p1, 8, pa3);
;     ...
; }
; template <int KB>
; __device__ __forceinline__ void qkt(f32x16& p0, f32x16& p1, const char* K_lds, int r32, int hi, const bf16x8* qr) {
;     p0 = f32x16{}; p1 = f32x16{};
;     const char* kb[4];
; #pragma unroll
;     for (int dd = 0; dd < 4; ++dd) kb[dd] = K_lds + KB * SHM_K + KSWZ(r32, (dd * 16 + hi * 8) * 2);
; #pragma unroll
;     for (int d0 = 0; d0 < 8; ++d0) { const char* a = kb[d0 & 3] + (d0 >> 2) * 128;
;         bf16x8 b0 = *reinterpret_cast<const bf16x8*>(a);
;         bf16x8 b1 = *reinterpret_cast<const bf16x8*>(a + 32 * 256);
;         p0 = __builtin_amdgcn_mfma_f32_32x32x16_bf16(b0, qr[d0], p0, 0, 0, 0);
;         p1 = __builtin_amdgcn_mfma_f32_32x32x16_bf16(b1, qr[d0], p1, 0, 0, 0); }
; }
.Lmy_hs1_nov:
	s_mov_b32 s100, 0
	ds_read_b128 v[66:69], v169 offset:49152
	ds_read_b128 v[70:73], v169 offset:57344
	ds_read_b128 v[100:103], v193 offset:49152
	ds_read_b128 v[136:139], v193 offset:57344
	s_waitcnt lgkmcnt(3)
	v_mfma_f32_32x32x16_bf16 v[82:97], v[66:69], v[132:135], 0
	v_add_f32_e32 v148, 0, v231
	v_add_f32_e32 v148, v233, v148
	v_add_f32_e32 v148, v229, v148
	v_add_f32_e32 v148, v232, v148
	v_add_f32_e32 v148, v228, v148
	s_waitcnt lgkmcnt(2)
	v_mfma_f32_32x32x16_bf16 v[66:81], v[70:73], v[132:135], 0
	v_add_f32_e32 v148, v230, v148
	v_add_f32_e32 v148, v226, v148
	v_add_f32_e32 v148, v227, v148
	v_add_f32_e32 v148, v223, v148
	v_add_f32_e32 v148, v225, v148
	s_waitcnt lgkmcnt(1)
	v_mfma_f32_32x32x16_bf16 v[82:97], v[100:103], v[128:131], v[82:97]
	v_add_f32_e32 v148, v209, v148
	v_add_f32_e32 v148, v224, v148
	v_add_f32_e32 v148, v206, v148
	v_add_f32_e32 v148, v208, v148
	v_add_f32_e32 v148, v205, v148
	s_waitcnt lgkmcnt(0)
	v_mfma_f32_32x32x16_bf16 v[66:81], v[136:139], v[128:131], v[66:81]
	v_add_f32_e32 v148, v207, v148
	v_exp_f32_e32 v140, v152
	v_exp_f32_e32 v141, v153
	v_exp_f32_e32 v142, v180
	v_exp_f32_e32 v143, v181
	ds_read_b128 v[100:103], v194 offset:49152
	ds_read_b128 v[136:139], v194 offset:57344
	s_waitcnt lgkmcnt(1)
	v_mfma_f32_32x32x16_bf16 v[82:97], v[100:103], v[124:127], v[82:97]
	v_exp_f32_e32 v144, v160
	v_exp_f32_e32 v145, v161
	v_exp_f32_e32 v146, v154
	v_exp_f32_e32 v147, v155
	v_exp_f32_e32 v178, v178
	s_waitcnt lgkmcnt(0)
	v_mfma_f32_32x32x16_bf16 v[66:81], v[136:139], v[124:127], v[66:81]
	v_exp_f32_e32 v179, v179
	v_exp_f32_e32 v162, v162
	v_exp_f32_e32 v163, v163
	v_add_f32_e32 v148, v178, v148
	v_add_f32_e32 v148, v179, v148
	ds_read_b128 v[100:103], v195 offset:49152
	ds_read_b128 v[136:139], v195 offset:57344
	s_waitcnt lgkmcnt(1)
	v_mfma_f32_32x32x16_bf16 v[82:97], v[100:103], v[120:123], v[82:97]
	v_add_f32_e32 v148, v162, v148
	v_exp_f32_e32 v158, v158
	v_exp_f32_e32 v159, v159
	v_exp_f32_e32 v156, v156
	v_exp_f32_e32 v157, v157
	s_waitcnt lgkmcnt(0)
	v_mfma_f32_32x32x16_bf16 v[66:81], v[136:139], v[120:123], v[66:81]
	v_add_f32_e32 v148, v163, v148
	v_add_f32_e32 v148, v158, v148
	v_add_f32_e32 v148, v159, v148
	v_add_f32_e32 v148, v156, v148
	v_add_f32_e32 v148, v157, v148
	ds_read_b128 v[100:103], v169 offset:49280
	ds_read_b128 v[136:139], v169 offset:57472
	s_waitcnt lgkmcnt(1)
	v_mfma_f32_32x32x16_bf16 v[82:97], v[100:103], v[116:119], v[82:97]
	v_add_f32_e32 v148, v140, v148
	v_add_f32_e32 v148, v141, v148
	v_add_f32_e32 v148, v142, v148
	v_add_f32_e32 v148, v143, v148
	v_add_f32_e32 v148, v144, v148
	s_waitcnt lgkmcnt(0)
	v_mfma_f32_32x32x16_bf16 v[66:81], v[136:139], v[116:119], v[66:81]
	v_add_f32_e32 v148, v145, v148
	v_add_f32_e32 v148, v146, v148
	v_add_f32_e32 v199, v147, v148
	v_mov_b32_e32 v200, v199
	s_nop 1
	v_permlane32_swap_b32_e32 v199, v200
	v_cvt_pk_bf16_f32 v148, v231, v233
	ds_read_b128 v[100:103], v193 offset:49280
	ds_read_b128 v[136:139], v193 offset:57472
	s_waitcnt lgkmcnt(1)
	v_mfma_f32_32x32x16_bf16 v[82:97], v[100:103], v[112:115], v[82:97]
	v_cvt_pk_bf16_f32 v149, v229, v232
	v_cvt_pk_bf16_f32 v150, v228, v230
	v_cvt_pk_bf16_f32 v151, v226, v227
	v_cvt_pk_bf16_f32 v152, v223, v225
	v_cvt_pk_bf16_f32 v153, v209, v224
	s_waitcnt lgkmcnt(0)
	v_mfma_f32_32x32x16_bf16 v[66:81], v[136:139], v[112:115], v[66:81]
	v_cvt_pk_bf16_f32 v154, v206, v208
	v_cvt_pk_bf16_f32 v155, v205, v207
	v_cvt_pk_bf16_f32 v158, v158, v159
	v_cvt_pk_bf16_f32 v159, v156, v157
	v_cvt_pk_bf16_f32 v156, v178, v179
	ds_read_b128 v[100:103], v194 offset:49280
	ds_read_b128 v[136:139], v194 offset:57472
	s_waitcnt lgkmcnt(1)
	v_mfma_f32_32x32x16_bf16 v[82:97], v[100:103], v[108:111], v[82:97]
	v_cvt_pk_bf16_f32 v157, v162, v163
	v_cvt_pk_bf16_f32 v160, v140, v141
	v_cvt_pk_bf16_f32 v161, v142, v143
	v_cvt_pk_bf16_f32 v162, v144, v145
	v_cvt_pk_bf16_f32 v163, v146, v147
	s_waitcnt lgkmcnt(0)
	v_mfma_f32_32x32x16_bf16 v[66:81], v[136:139], v[108:111], v[66:81]
	s_nop 0
	v_permlane32_swap_b32_e32 v148, v150
	v_permlane32_swap_b32_e32 v149, v151
	v_permlane32_swap_b32_e32 v152, v154
	v_permlane32_swap_b32_e32 v153, v155
	ds_read_b128 v[100:103], v195 offset:49280
	ds_read_b128 v[136:139], v195 offset:57472
	ds_read_b64_tr_b16 v[172:173], v185 offset:0
	ds_read_b64_tr_b16 v[174:175], v185 offset:0x800
	ds_read_b64_tr_b16 v[202:203], v185 offset:0x1000
	ds_read_b64_tr_b16 v[204:205], v185 offset:0x1800
	ds_read_b64_tr_b16 v[206:207], v185 offset:0x2000
	ds_read_b64_tr_b16 v[208:209], v185 offset:0x2800
	ds_read_b64_tr_b16 v[224:225], v185 offset:0x3000
	ds_read_b64_tr_b16 v[226:227], v185 offset:0x3800
	s_waitcnt lgkmcnt(9)
	v_mfma_f32_32x32x16_bf16 v[82:97], v[100:103], v[104:107], v[82:97]
	v_permlane32_swap_b32_e32 v156, v158
	v_permlane32_swap_b32_e32 v157, v159
	v_permlane32_swap_b32_e32 v160, v162
	v_permlane32_swap_b32_e32 v161, v163
	s_waitcnt lgkmcnt(8)
	v_mfma_f32_32x32x16_bf16 v[66:81], v[136:139], v[104:107], v[66:81]
	v_add_u32_e32 v178, s7, v166
	v_add_u32_e32 v100, 1, v178
	v_add_u32_e32 v102, 33, v178
	v_ashrrev_i32_e32 v101, 31, v100
	v_ashrrev_i32_e32 v103, 31, v102
	v_lshlrev_b64 v[140:141], 8, v[100:101]
	v_lshlrev_b64 v[142:143], 8, v[102:103]
	v_lshl_add_u64 v[100:101], v[170:171], 0, v[140:141]
	v_lshl_add_u64 v[136:137], v[170:171], 0, v[142:143]
	v_lshl_add_u64 v[140:141], v[176:177], 0, v[140:141]
	v_lshl_add_u64 v[144:145], v[176:177], 0, v[142:143]
	global_load_dwordx4 v[100:103], v[100:101], off
	s_nop 0
	global_load_dwordx4 v[136:139], v[136:137], off
	s_nop 0
	global_load_dwordx4 v[140:143], v[140:141], off
	s_nop 0
	global_load_dwordx4 v[144:147], v[144:145], off
	s_waitcnt lgkmcnt(0)
; __device__ __forceinline__ void mask_tile(f32x16& p0, f32x16& p1, int dq, unsigned W) {
;     const float NEG = -__builtin_inff();
; #pragma unroll
;     for (int r = 0; r < 16; ++r) {
;         const int c = (r & 3) + 8 * (r >> 2);
;         if ((unsigned)(dq - c) >= W) p0[r] = NEG;
;         if ((unsigned)(dq - c - 32) >= W) p1[r] = NEG;
;     }
; }
; template <int VB>
; __device__ __forceinline__ void pv_tile(f32x16* o, int vb0, bf16x8 pa0, bf16x8 pa1, bf16x8 pa2, bf16x8 pa3) {
;     ...
;     PV_D0(0); PV_D0(1); PV_D0(2); PV_D0(3);
	s_nop 0
	v_mfma_f32_32x32x16_bf16 v[50:65], v[148:151], v[172:175], v[50:65]
	ds_read_b64_tr_b16 v[172:173], v185 offset:0x200
	ds_read_b64_tr_b16 v[174:175], v185 offset:0xa00
	v_mfma_f32_32x32x16_bf16 v[50:65], v[152:155], v[202:205], v[50:65]
	ds_read_b64_tr_b16 v[202:203], v185 offset:0x1200
	ds_read_b64_tr_b16 v[204:205], v185 offset:0x1a00
	v_mfma_f32_32x32x16_bf16 v[50:65], v[156:159], v[206:209], v[50:65]
	ds_read_b64_tr_b16 v[206:207], v185 offset:0x2200
	ds_read_b64_tr_b16 v[208:209], v185 offset:0x2a00
	v_mfma_f32_32x32x16_bf16 v[50:65], v[160:163], v[224:227], v[50:65]
	ds_read_b64_tr_b16 v[224:225], v185 offset:0x3200
	ds_read_b64_tr_b16 v[226:227], v185 offset:0x3a00
	s_waitcnt lgkmcnt(0)
	v_mfma_f32_32x32x16_bf16 v[34:49], v[148:151], v[172:175], v[34:49]
	ds_read_b64_tr_b16 v[172:173], v185 offset:0x400
	ds_read_b64_tr_b16 v[174:175], v185 offset:0xc00
	v_mfma_f32_32x32x16_bf16 v[34:49], v[152:155], v[202:205], v[34:49]
	ds_read_b64_tr_b16 v[202:203], v185 offset:0x1400
	ds_read_b64_tr_b16 v[204:205], v185 offset:0x1c00
	v_mfma_f32_32x32x16_bf16 v[34:49], v[156:159], v[206:209], v[34:49]
	ds_read_b64_tr_b16 v[206:207], v185 offset:0x2400
	ds_read_b64_tr_b16 v[208:209], v185 offset:0x2c00
	v_mfma_f32_32x32x16_bf16 v[34:49], v[160:163], v[224:227], v[34:49]
	ds_read_b64_tr_b16 v[224:225], v185 offset:0x3400
	ds_read_b64_tr_b16 v[226:227], v185 offset:0x3c00
	s_waitcnt lgkmcnt(0)
	v_mfma_f32_32x32x16_bf16 v[18:33], v[148:151], v[172:175], v[18:33]
	ds_read_b64_tr_b16 v[172:173], v185 offset:0x600
	ds_read_b64_tr_b16 v[174:175], v185 offset:0xe00
	v_mfma_f32_32x32x16_bf16 v[18:33], v[152:155], v[202:205], v[18:33]
	ds_read_b64_tr_b16 v[202:203], v185 offset:0x1600
	ds_read_b64_tr_b16 v[204:205], v185 offset:0x1e00
	v_mfma_f32_32x32x16_bf16 v[18:33], v[156:159], v[206:209], v[18:33]
	ds_read_b64_tr_b16 v[206:207], v185 offset:0x2600
	ds_read_b64_tr_b16 v[208:209], v185 offset:0x2e00
	v_mfma_f32_32x32x16_bf16 v[18:33], v[160:163], v[224:227], v[18:33]
	ds_read_b64_tr_b16 v[224:225], v185 offset:0x3600
	ds_read_b64_tr_b16 v[226:227], v185 offset:0x3e00
	s_waitcnt lgkmcnt(0)
	v_mfma_f32_32x32x16_bf16 v[2:17], v[148:151], v[172:175], v[2:17]
	s_cmp_le_i32 s7, s6
	v_mfma_f32_32x32x16_bf16 v[2:17], v[152:155], v[202:205], v[2:17]
	v_mfma_f32_32x32x16_bf16 v[2:17], v[156:159], v[206:209], v[2:17]
	v_mfma_f32_32x32x16_bf16 v[2:17], v[160:163], v[224:227], v[2:17]
	s_cbranch_scc1 .LBB0_91
	v_add_u32_e32 v148, 0x4000007b, v197
	v_cmp_gt_u32_e32 vcc, 2.0, v148
	v_add_u32_e32 v148, 0x5b, v197
	s_nop 0
	v_cndmask_b32_e32 v82, v220, v82, vcc
	v_cmp_lt_u32_e32 vcc, s33, v148
	v_add_u32_e32 v148, 0x7a, v197
	s_nop 0
	v_cndmask_b32_e32 v66, v220, v66, vcc
	v_cmp_lt_u32_e32 vcc, s33, v148
	v_add_u32_e32 v148, 0x5a, v197
	s_nop 0
	v_cndmask_b32_e32 v83, v220, v83, vcc
	v_cmp_lt_u32_e32 vcc, s33, v148
	v_add_u32_e32 v148, 0x79, v197
	s_nop 0
	v_cndmask_b32_e32 v67, v220, v67, vcc
	v_cmp_lt_u32_e32 vcc, s33, v148
	v_add_u32_e32 v148, 0x59, v197
	s_nop 0
	v_cndmask_b32_e32 v84, v220, v84, vcc
	v_cmp_lt_u32_e32 vcc, s33, v148
	v_add_u32_e32 v148, 0x78, v197
	s_nop 0
	v_cndmask_b32_e32 v68, v220, v68, vcc
	v_cmp_lt_u32_e32 vcc, s33, v148
	v_add_u32_e32 v148, 0x58, v197
	s_nop 0
	v_cndmask_b32_e32 v85, v220, v85, vcc
	v_cmp_lt_u32_e32 vcc, s33, v148
	v_add_u32_e32 v148, 0x73, v197
	s_nop 0
	v_cndmask_b32_e32 v69, v220, v69, vcc
	v_cmp_lt_u32_e32 vcc, s33, v148
	v_add_u32_e32 v148, 0x53, v197
	s_nop 0
	v_cndmask_b32_e32 v86, v220, v86, vcc
	v_cmp_lt_u32_e32 vcc, s33, v148
	v_add_u32_e32 v148, 0x72, v197
	s_nop 0
	v_cndmask_b32_e32 v70, v220, v70, vcc
	v_cmp_lt_u32_e32 vcc, s33, v148
	v_add_u32_e32 v148, 0x52, v197
	s_nop 0
	v_cndmask_b32_e32 v87, v220, v87, vcc
	v_cmp_lt_u32_e32 vcc, s33, v148
	v_add_u32_e32 v148, 0x71, v197
	s_nop 0
	v_cndmask_b32_e32 v71, v220, v71, vcc
	v_cmp_lt_u32_e32 vcc, s33, v148
	v_add_u32_e32 v148, 0x51, v197
	s_nop 0
	v_cndmask_b32_e32 v88, v220, v88, vcc
	v_cmp_lt_u32_e32 vcc, s33, v148
	v_add_u32_e32 v148, 0x70, v197
	s_nop 0
	v_cndmask_b32_e32 v72, v220, v72, vcc
	v_cmp_lt_u32_e32 vcc, s33, v148
	v_add_u32_e32 v148, 0x50, v197
	s_nop 0
	v_cndmask_b32_e32 v89, v220, v89, vcc
	v_cmp_lt_u32_e32 vcc, s33, v148
	v_add_u32_e32 v148, 0x6b, v197
	s_nop 0
	v_cndmask_b32_e32 v73, v220, v73, vcc
	v_cmp_lt_u32_e32 vcc, s33, v148
	v_add_u32_e32 v148, 0x4b, v197
	s_nop 0
	v_cndmask_b32_e32 v90, v220, v90, vcc
	v_cmp_lt_u32_e32 vcc, s33, v148
	v_add_u32_e32 v148, 0x6a, v197
	s_nop 0
	v_cndmask_b32_e32 v74, v220, v74, vcc
	v_cmp_lt_u32_e32 vcc, s33, v148
	v_add_u32_e32 v148, 0x4a, v197
	s_nop 0
	v_cndmask_b32_e32 v91, v220, v91, vcc
	v_cmp_lt_u32_e32 vcc, s33, v148
	v_add_u32_e32 v148, 0x69, v197
	s_nop 0
	v_cndmask_b32_e32 v75, v220, v75, vcc
	v_cmp_lt_u32_e32 vcc, s33, v148
	v_add_u32_e32 v148, 0x49, v197
	s_nop 0
	v_cndmask_b32_e32 v92, v220, v92, vcc
	v_cmp_lt_u32_e32 vcc, s33, v148
	v_add_u32_e32 v148, 0x68, v197
	s_nop 0
	v_cndmask_b32_e32 v76, v220, v76, vcc
	v_cmp_lt_u32_e32 vcc, s33, v148
	v_add_u32_e32 v148, 0x48, v197
	s_nop 0
	v_cndmask_b32_e32 v93, v220, v93, vcc
	v_cmp_lt_u32_e32 vcc, s33, v148
	v_add_u32_e32 v148, 0x63, v197
	s_nop 0
	v_cndmask_b32_e32 v77, v220, v77, vcc
	v_cmp_lt_u32_e32 vcc, s33, v148
	v_add_u32_e32 v148, 0x43, v197
	s_nop 0
	v_cndmask_b32_e32 v94, v220, v94, vcc
	v_cmp_lt_u32_e32 vcc, s33, v148
	v_add_u32_e32 v148, 0x62, v197
	s_nop 0
	v_cndmask_b32_e32 v78, v220, v78, vcc
	v_cmp_lt_u32_e32 vcc, s33, v148
	v_add_u32_e32 v148, 0x42, v197
	s_nop 0
	v_cndmask_b32_e32 v95, v220, v95, vcc
	v_cmp_lt_u32_e32 vcc, s33, v148
	v_add_u32_e32 v148, 0x61, v197
	s_nop 0
	v_cndmask_b32_e32 v79, v220, v79, vcc
	v_cmp_lt_u32_e32 vcc, s33, v148
	v_add_u32_e32 v148, 0x41, v197
	s_nop 0
	v_cndmask_b32_e32 v96, v220, v96, vcc
	v_cmp_lt_u32_e32 vcc, s33, v148
	v_add_u32_e32 v148, 0x60, v197
	s_nop 0
	v_cndmask_b32_e32 v80, v220, v80, vcc
	v_cmp_lt_u32_e32 vcc, s33, v148
	v_add_u32_e32 v148, 64, v197
	s_nop 0
	v_cndmask_b32_e32 v97, v220, v97, vcc
	v_cmp_lt_u32_e32 vcc, s33, v148
	s_nop 1
	v_cndmask_b32_e32 v81, v220, v81, vcc

; __device__ __forceinline__ void partialSM(f32x16& p0, f32x16& p1, float& m_reg, float& mn, float& alpha, bool rs) {
;     float pmax = p0[0]; for (int r = 1; r < 16; ++r) pmax = fmaxf(pmax, p0[r]); for (int r = 0; r < 16; ++r) pmax = fmaxf(pmax, p1[r]);
;     if (!rs) pmax = -__builtin_inff();
;     { auto rr = __builtin_amdgcn_permlane32_swap(__float_as_uint(pmax), __float_as_uint(pmax), false, false);
;       pmax = fmaxf(__uint_as_float(rr[0]), __uint_as_float(rr[1])); }
;     constexpr float C2 = 1.4426950408889634f * SCALE;
;     if (__builtin_expect(__all((pmax - m_reg) * SCALE <= THR), 1)) { mn = m_reg; alpha = 1.f; }
;     else { mn = fmaxf(m_reg, pmax); alpha = __builtin_amdgcn_exp2f((m_reg - mn) * C2); m_reg = mn; }
;     const float mnL = rs ? -mn * C2 : -__builtin_inff();
;     for (int r = 0; r < 16; ++r) p0[r] = fmaf(p0[r], C2, mnL); for (int r = 0; r < 16; ++r) p1[r] = fmaf(p1[r], C2, mnL);
;     for (int r = 0; r < 16; ++r) p0[r] = __builtin_amdgcn_exp2f(p0[r]);
; }
; __device__ __forceinline__ void finishSM(f32x16& p0, f32x16& p1, float alpha, float& l_reg, bf16x8& pa0, bf16x8& pa1, bf16x8& pa2, bf16x8& pa3) {
;     for (int r = 0; r < 16; ++r) p1[r] = __builtin_amdgcn_exp2f(p1[r]);
;     float ps = 0; for (int r = 0; r < 16; ++r) ps += p0[r]; for (int r = 0; r < 16; ++r) ps += p1[r];
;     { auto rr = __builtin_amdgcn_permlane32_swap(__float_as_uint(ps), __float_as_uint(ps), false, false);
;       ps = __uint_as_float(rr[0]) + __uint_as_float(rr[1]); }
;     l_reg = l_reg * alpha + ps;
;     ...
;     PK4(p0, 0, pa0); PK4(p0, 8, pa1); PK4(p1, 0, pa2); PK4(p1, 8, pa3);
;     ...
; }
; template <int KB>
; __device__ __forceinline__ void qkt(f32x16& p0, f32x16& p1, const char* K_lds, int r32, int hi, const bf16x8* qr) {
;     p0 = f32x16{}; p1 = f32x16{};
;     const char* kb[4];
; #pragma unroll
;     for (int dd = 0; dd < 4; ++dd) kb[dd] = K_lds + KB * SHM_K + KSWZ(r32, (dd * 16 + hi * 8) * 2);
; #pragma unroll
;     for (int d0 = 0; d0 < 8; ++d0) { const char* a = kb[d0 & 3] + (d0 >> 2) * 128;
;         bf16x8 b0 = *reinterpret_cast<const bf16x8*>(a);
;         bf16x8 b1 = *reinterpret_cast<const bf16x8*>(a + 32 * 256);
;         p0 = __builtin_amdgcn_mfma_f32_32x32x16_bf16(b0, qr[d0], p0, 0, 0, 0);
;         p1 = __builtin_amdgcn_mfma_f32_32x32x16_bf16(b1, qr[d0], p1, 0, 0, 0); }
; }
.LBB0_95:
	v_cndmask_b32_e64 v179, v148, v198, s[42:43]
	v_mul_f32_e32 v148, 0xbe0293ee, v179
	v_cndmask_b32_e64 v180, v220, v148, s[40:41]
	v_fmamk_f32 v82, v82, 0x3e0293ee, v180
	v_fmamk_f32 v83, v83, 0x3e0293ee, v180
	v_fmamk_f32 v84, v84, 0x3e0293ee, v180
	v_fmamk_f32 v85, v85, 0x3e0293ee, v180
	v_fmamk_f32 v86, v86, 0x3e0293ee, v180
	v_fmamk_f32 v87, v87, 0x3e0293ee, v180
	v_fmamk_f32 v88, v88, 0x3e0293ee, v180
	v_fmamk_f32 v89, v89, 0x3e0293ee, v180
	v_fmamk_f32 v90, v90, 0x3e0293ee, v180
	v_fmamk_f32 v91, v91, 0x3e0293ee, v180
	v_fmamk_f32 v92, v92, 0x3e0293ee, v180
	v_fmamk_f32 v93, v93, 0x3e0293ee, v180
	v_fmamk_f32 v94, v94, 0x3e0293ee, v180
	v_fmamk_f32 v95, v95, 0x3e0293ee, v180
	v_fmamk_f32 v96, v96, 0x3e0293ee, v180
	v_fmamk_f32 v97, v97, 0x3e0293ee, v180
	v_exp_f32_e32 v148, v82
	v_exp_f32_e32 v163, v83
	v_exp_f32_e32 v149, v84
	v_exp_f32_e32 v162, v85
	v_exp_f32_e32 v150, v86
	v_exp_f32_e32 v161, v87
	v_exp_f32_e32 v151, v88
	v_exp_f32_e32 v160, v89
	v_exp_f32_e32 v152, v90
	v_exp_f32_e32 v159, v91
	v_exp_f32_e32 v153, v92
	v_exp_f32_e32 v158, v93
	v_exp_f32_e32 v154, v94
	v_exp_f32_e32 v157, v95
	v_exp_f32_e32 v155, v96
	v_exp_f32_e32 v156, v97
	v_fmamk_f32 v203, v73, 0x3e0293ee, v180
	v_fmamk_f32 v204, v74, 0x3e0293ee, v180
	v_fmamk_f32 v208, v66, 0x3e0293ee, v180
	v_fmamk_f32 v209, v67, 0x3e0293ee, v180
	v_fmamk_f32 v223, v68, 0x3e0293ee, v180
	v_fmamk_f32 v224, v69, 0x3e0293ee, v180
	v_fmamk_f32 v225, v70, 0x3e0293ee, v180
	v_fmamk_f32 v198, v71, 0x3e0293ee, v180
	v_fmamk_f32 v201, v72, 0x3e0293ee, v180
	v_fmamk_f32 v205, v75, 0x3e0293ee, v180
	v_fmamk_f32 v206, v76, 0x3e0293ee, v180
	v_fmamk_f32 v207, v77, 0x3e0293ee, v180
	v_fmamk_f32 v181, v78, 0x3e0293ee, v180
	v_fmamk_f32 v226, v79, 0x3e0293ee, v180
	v_fmamk_f32 v227, v80, 0x3e0293ee, v180
	v_fmac_f32_e32 v180, 0x3e0293ee, v81
	s_waitcnt lgkmcnt(0)
	s_barrier
	s_waitcnt vmcnt(0)
	ds_write_b128 v191, v[100:103]
	ds_write_b128 v192, v[136:139]
	ds_read_b128 v[66:69], v169 offset:32768
	ds_read_b128 v[70:73], v169 offset:40960
	ds_read_b128 v[172:175], v193 offset:32768
	ds_read_b128 v[228:231], v193 offset:40960
	s_waitcnt lgkmcnt(3)
	v_mfma_f32_32x32x16_bf16 v[82:97], v[66:69], v[132:135], 0
	v_exp_f32_e32 v198, v198
	v_exp_f32_e32 v201, v201
	v_exp_f32_e32 v214, v204
	v_exp_f32_e32 v205, v205
	v_exp_f32_e32 v206, v206
	s_waitcnt lgkmcnt(2)
	v_mfma_f32_32x32x16_bf16 v[66:81], v[70:73], v[132:135], 0
	v_exp_f32_e32 v207, v207
	v_exp_f32_e32 v181, v181
	v_exp_f32_e32 v215, v226
	v_exp_f32_e32 v216, v227
	v_exp_f32_e32 v180, v180
	s_waitcnt lgkmcnt(1)
	v_mfma_f32_32x32x16_bf16 v[82:97], v[172:175], v[128:131], v[82:97]
	v_exp_f32_e32 v218, v209
	v_exp_f32_e32 v209, v203
	v_add_f32_e32 v203, 0, v148
	v_add_f32_e32 v203, v163, v203
	v_add_f32_e32 v203, v149, v203
	s_waitcnt lgkmcnt(0)
	v_mfma_f32_32x32x16_bf16 v[66:81], v[228:231], v[128:131], v[66:81]
	v_add_f32_e32 v203, v162, v203
	v_add_f32_e32 v203, v150, v203
	v_add_f32_e32 v203, v161, v203
	v_add_f32_e32 v203, v151, v203
	v_add_f32_e32 v203, v160, v203
	ds_read_b128 v[172:175], v194 offset:32768
	ds_read_b128 v[228:231], v194 offset:40960
	s_waitcnt lgkmcnt(1)
	v_mfma_f32_32x32x16_bf16 v[82:97], v[172:175], v[124:127], v[82:97]
	v_add_f32_e32 v203, v152, v203
	v_add_f32_e32 v203, v159, v203
	v_add_f32_e32 v203, v153, v203
	v_add_f32_e32 v203, v158, v203
	v_exp_f32_e32 v217, v208
	s_waitcnt lgkmcnt(0)
	v_mfma_f32_32x32x16_bf16 v[66:81], v[228:231], v[124:127], v[66:81]
	v_add_f32_e32 v203, v154, v203
	v_add_f32_e32 v203, v157, v203
	v_exp_f32_e32 v219, v223
	v_add_f32_e32 v203, v155, v203
	v_exp_f32_e32 v222, v224
	ds_read_b128 v[172:175], v195 offset:32768
	ds_read_b128 v[228:231], v195 offset:40960
	s_waitcnt lgkmcnt(1)
	v_mfma_f32_32x32x16_bf16 v[82:97], v[172:175], v[120:123], v[82:97]
	v_add_f32_e32 v203, v156, v203
	v_exp_f32_e32 v208, v225
	v_add_f32_e32 v203, v217, v203
	v_add_f32_e32 v203, v218, v203
	v_add_f32_e32 v203, v219, v203
	s_waitcnt lgkmcnt(0)
	v_mfma_f32_32x32x16_bf16 v[66:81], v[228:231], v[120:123], v[66:81]
	v_add_f32_e32 v203, v222, v203
	v_add_f32_e32 v203, v208, v203
	v_add_f32_e32 v203, v198, v203
	v_add_f32_e32 v203, v201, v203
	v_add_f32_e32 v203, v209, v203
	ds_read_b128 v[172:175], v169 offset:32896
	ds_read_b128 v[228:231], v169 offset:41088
	s_waitcnt lgkmcnt(1)
	v_mfma_f32_32x32x16_bf16 v[82:97], v[172:175], v[116:119], v[82:97]
	v_add_f32_e32 v203, v214, v203
	v_add_f32_e32 v203, v205, v203
	v_add_f32_e32 v203, v206, v203
	v_add_f32_e32 v203, v207, v203
	v_add_f32_e32 v203, v181, v203
	s_waitcnt lgkmcnt(0)
	v_mfma_f32_32x32x16_bf16 v[66:81], v[228:231], v[116:119], v[66:81]
	v_add_f32_e32 v203, v215, v203
	v_add_f32_e32 v203, v216, v203
	v_add_f32_e32 v203, v180, v203
	v_mov_b32_e32 v204, v203
	v_cvt_pk_bf16_f32 v148, v148, v163
	ds_read_b128 v[172:175], v193 offset:32896
	ds_read_b128 v[228:231], v193 offset:41088
	s_waitcnt lgkmcnt(1)
	v_mfma_f32_32x32x16_bf16 v[82:97], v[172:175], v[112:115], v[82:97]
	v_cvt_pk_bf16_f32 v149, v149, v162
	v_cvt_pk_bf16_f32 v150, v150, v161
	v_cvt_pk_bf16_f32 v151, v151, v160
	v_cvt_pk_bf16_f32 v152, v152, v159
	v_cvt_pk_bf16_f32 v153, v153, v158
	s_waitcnt lgkmcnt(0)
	v_mfma_f32_32x32x16_bf16 v[66:81], v[228:231], v[112:115], v[66:81]
	v_cvt_pk_bf16_f32 v154, v154, v157
	v_cvt_pk_bf16_f32 v155, v155, v156
	v_cvt_pk_bf16_f32 v156, v217, v218
	v_cvt_pk_bf16_f32 v157, v219, v222
	v_cvt_pk_bf16_f32 v158, v208, v198
	ds_read_b128 v[172:175], v194 offset:32896
	ds_read_b128 v[228:231], v194 offset:41088
	s_waitcnt lgkmcnt(1)
	v_mfma_f32_32x32x16_bf16 v[82:97], v[172:175], v[108:111], v[82:97]
	v_cvt_pk_bf16_f32 v159, v201, v209
	v_cvt_pk_bf16_f32 v160, v214, v205
	v_cvt_pk_bf16_f32 v161, v206, v207
	v_cvt_pk_bf16_f32 v162, v181, v215
	v_cvt_pk_bf16_f32 v163, v216, v180
	s_waitcnt lgkmcnt(0)
	v_mfma_f32_32x32x16_bf16 v[66:81], v[228:231], v[108:111], v[66:81]
	s_nop 1
	v_permlane32_swap_b32_e32 v203, v204
	v_permlane32_swap_b32_e32 v148, v150
	v_permlane32_swap_b32_e32 v149, v151
	v_permlane32_swap_b32_e32 v152, v154
	v_permlane32_swap_b32_e32 v153, v155
	ds_read_b128 v[172:175], v195 offset:32896
	ds_read_b128 v[228:231], v195 offset:41088
	ds_read_b64_tr_b16 v[206:207], v185 offset:0x5000
	ds_read_b64_tr_b16 v[208:209], v185 offset:0x5800
	ds_read_b64_tr_b16 v[224:225], v185 offset:0x6000
	ds_read_b64_tr_b16 v[226:227], v185 offset:0x6800
	s_waitcnt lgkmcnt(5)
	v_mfma_f32_32x32x16_bf16 v[82:97], v[172:175], v[104:107], v[82:97]
	v_permlane32_swap_b32_e32 v156, v158
	v_permlane32_swap_b32_e32 v157, v159
	v_permlane32_swap_b32_e32 v160, v162
	v_permlane32_swap_b32_e32 v161, v163
	s_waitcnt lgkmcnt(4)
	v_mfma_f32_32x32x16_bf16 v[66:81], v[228:231], v[104:107], v[66:81]
	ds_read_b64_tr_b16 v[172:173], v185 offset:0x4000
	ds_read_b64_tr_b16 v[174:175], v185 offset:0x4800
	ds_read_b64_tr_b16 v[228:229], v185 offset:0x7000
	ds_read_b64_tr_b16 v[230:231], v185 offset:0x7800
	s_cmp_lt_u32 s3, s2
	s_cselect_b64 s[22:23], -1, 0
	s_cmp_ge_u32 s3, s2
	s_cbranch_scc1 .LBB0_97
; template <int VB>
; __device__ __forceinline__ void pv_tile(f32x16* o, int vb0, bf16x8 pa0, bf16x8 pa1, bf16x8 pa2, bf16x8 pa3) {
;     ...
;     PV_D0(0); PV_D0(1); PV_D0(2); PV_D0(3);
	v_add_u32_e32 v242, 0x41, v178
	v_add_u32_e32 v246, 0x61, v178
	v_ashrrev_i32_e32 v243, 31, v242
	v_ashrrev_i32_e32 v247, 31, v246
	v_lshlrev_b64 v[140:141], 8, v[242:243]
	v_lshlrev_b64 v[142:143], 8, v[246:247]
	v_lshl_add_u64 v[242:243], v[170:171], 0, v[140:141]
	v_lshl_add_u64 v[246:247], v[170:171], 0, v[142:143]
	v_lshl_add_u64 v[140:141], v[176:177], 0, v[140:141]
	v_lshl_add_u64 v[144:145], v[176:177], 0, v[142:143]
	global_load_dwordx4 v[242:245], v[242:243], off
	s_nop 0
	global_load_dwordx4 v[246:249], v[246:247], off
	s_nop 0
	global_load_dwordx4 v[140:143], v[140:141], off
	s_nop 0
	global_load_dwordx4 v[144:147], v[144:145], off
	s_mov_b32 s100, 1
.LBB0_97:
	s_waitcnt lgkmcnt(0)
	s_nop 0
	v_mfma_f32_32x32x16_bf16 v[50:65], v[148:151], v[172:175], v[50:65]
	ds_read_b64_tr_b16 v[172:173], v185 offset:0x4200
	ds_read_b64_tr_b16 v[174:175], v185 offset:0x4a00
	v_mfma_f32_32x32x16_bf16 v[50:65], v[152:155], v[206:209], v[50:65]
	ds_read_b64_tr_b16 v[206:207], v185 offset:0x5200
	ds_read_b64_tr_b16 v[208:209], v185 offset:0x5a00
	v_mfma_f32_32x32x16_bf16 v[50:65], v[156:159], v[224:227], v[50:65]
	ds_read_b64_tr_b16 v[224:225], v185 offset:0x6200
	ds_read_b64_tr_b16 v[226:227], v185 offset:0x6a00
	v_mfma_f32_32x32x16_bf16 v[50:65], v[160:163], v[228:231], v[50:65]
	ds_read_b64_tr_b16 v[228:229], v185 offset:0x7200
	ds_read_b64_tr_b16 v[230:231], v185 offset:0x7a00
	s_waitcnt lgkmcnt(0)
	v_mfma_f32_32x32x16_bf16 v[34:49], v[148:151], v[172:175], v[34:49]
	ds_read_b64_tr_b16 v[172:173], v185 offset:0x4400
	ds_read_b64_tr_b16 v[174:175], v185 offset:0x4c00
	v_mfma_f32_32x32x16_bf16 v[34:49], v[152:155], v[206:209], v[34:49]
	ds_read_b64_tr_b16 v[206:207], v185 offset:0x5400
	ds_read_b64_tr_b16 v[208:209], v185 offset:0x5c00
	v_mfma_f32_32x32x16_bf16 v[34:49], v[156:159], v[224:227], v[34:49]
	ds_read_b64_tr_b16 v[224:225], v185 offset:0x6400
	ds_read_b64_tr_b16 v[226:227], v185 offset:0x6c00
	v_mfma_f32_32x32x16_bf16 v[34:49], v[160:163], v[228:231], v[34:49]
	ds_read_b64_tr_b16 v[228:229], v185 offset:0x7400
	ds_read_b64_tr_b16 v[230:231], v185 offset:0x7c00
	s_waitcnt lgkmcnt(0)
	v_mfma_f32_32x32x16_bf16 v[18:33], v[148:151], v[172:175], v[18:33]
	ds_read_b64_tr_b16 v[172:173], v185 offset:0x4600
	ds_read_b64_tr_b16 v[174:175], v185 offset:0x4e00
	v_mfma_f32_32x32x16_bf16 v[18:33], v[152:155], v[206:209], v[18:33]
	ds_read_b64_tr_b16 v[206:207], v185 offset:0x5600
	ds_read_b64_tr_b16 v[208:209], v185 offset:0x5e00
	v_mfma_f32_32x32x16_bf16 v[18:33], v[156:159], v[224:227], v[18:33]
	ds_read_b64_tr_b16 v[224:225], v185 offset:0x6600
	ds_read_b64_tr_b16 v[226:227], v185 offset:0x6e00
	v_mfma_f32_32x32x16_bf16 v[18:33], v[160:163], v[228:231], v[18:33]
	ds_read_b64_tr_b16 v[228:229], v185 offset:0x7600
	ds_read_b64_tr_b16 v[230:231], v185 offset:0x7e00
	s_waitcnt lgkmcnt(0)
	v_mfma_f32_32x32x16_bf16 v[2:17], v[148:151], v[172:175], v[2:17]
	s_add_i32 s0, s7, 64
	s_cmp_le_i32 s0, s6
	v_mfma_f32_32x32x16_bf16 v[2:17], v[152:155], v[206:209], v[2:17]
	v_mfma_f32_32x32x16_bf16 v[2:17], v[156:159], v[224:227], v[2:17]
	v_mfma_f32_32x32x16_bf16 v[2:17], v[160:163], v[228:231], v[2:17]
	s_cbranch_scc1 .LBB0_99
	v_add_u32_e32 v148, 0x4000003b, v197
	v_cmp_gt_u32_e32 vcc, 2.0, v148
	v_add_u32_e32 v148, 27, v197
	s_nop 0
	v_cndmask_b32_e32 v82, v220, v82, vcc
	v_cmp_lt_u32_e32 vcc, s33, v148
	v_add_u32_e32 v148, 58, v197
	s_nop 0
	v_cndmask_b32_e32 v66, v220, v66, vcc
	v_cmp_lt_u32_e32 vcc, s33, v148
	v_add_u32_e32 v148, 26, v197
	s_nop 0
	v_cndmask_b32_e32 v83, v220, v83, vcc
	v_cmp_lt_u32_e32 vcc, s33, v148
	v_add_u32_e32 v148, 57, v197
	s_nop 0
	v_cndmask_b32_e32 v67, v220, v67, vcc
	v_cmp_lt_u32_e32 vcc, s33, v148
	v_add_u32_e32 v148, 25, v197
	s_nop 0
	v_cndmask_b32_e32 v84, v220, v84, vcc
	v_cmp_lt_u32_e32 vcc, s33, v148
	v_add_u32_e32 v148, 56, v197
	s_nop 0
	v_cndmask_b32_e32 v68, v220, v68, vcc
	v_cmp_lt_u32_e32 vcc, s33, v148
	v_add_u32_e32 v148, 24, v197
	s_nop 0
	v_cndmask_b32_e32 v85, v220, v85, vcc
	v_cmp_lt_u32_e32 vcc, s33, v148
	v_add_u32_e32 v148, 51, v197
	s_nop 0
	v_cndmask_b32_e32 v69, v220, v69, vcc
	v_cmp_lt_u32_e32 vcc, s33, v148
	v_add_u32_e32 v148, 19, v197
	s_nop 0
	v_cndmask_b32_e32 v86, v220, v86, vcc
	v_cmp_lt_u32_e32 vcc, s33, v148
	v_add_u32_e32 v148, 50, v197
	s_nop 0
	v_cndmask_b32_e32 v70, v220, v70, vcc
	v_cmp_lt_u32_e32 vcc, s33, v148
	v_add_u32_e32 v148, 18, v197
	s_nop 0
	v_cndmask_b32_e32 v87, v220, v87, vcc
	v_cmp_lt_u32_e32 vcc, s33, v148
	v_add_u32_e32 v148, 49, v197
	s_nop 0
	v_cndmask_b32_e32 v71, v220, v71, vcc
	v_cmp_lt_u32_e32 vcc, s33, v148
	v_add_u32_e32 v148, 17, v197
	s_nop 0
	v_cndmask_b32_e32 v88, v220, v88, vcc
	v_cmp_lt_u32_e32 vcc, s33, v148
	v_add_u32_e32 v148, 48, v197
	s_nop 0
	v_cndmask_b32_e32 v72, v220, v72, vcc
	v_cmp_lt_u32_e32 vcc, s33, v148
	v_add_u32_e32 v148, 16, v197
	s_nop 0
	v_cndmask_b32_e32 v89, v220, v89, vcc
	v_cmp_lt_u32_e32 vcc, s33, v148
	v_add_u32_e32 v148, 43, v197
	s_nop 0
	v_cndmask_b32_e32 v73, v220, v73, vcc
	v_cmp_lt_u32_e32 vcc, s33, v148
	v_add_u32_e32 v148, 11, v197
	s_nop 0
	v_cndmask_b32_e32 v90, v220, v90, vcc
	v_cmp_lt_u32_e32 vcc, s33, v148
	v_add_u32_e32 v148, 42, v197
	s_nop 0
	v_cndmask_b32_e32 v74, v220, v74, vcc
	v_cmp_lt_u32_e32 vcc, s33, v148
	v_add_u32_e32 v148, 10, v197
	s_nop 0
	v_cndmask_b32_e32 v91, v220, v91, vcc
	v_cmp_lt_u32_e32 vcc, s33, v148
	v_add_u32_e32 v148, 41, v197
	s_nop 0
	v_cndmask_b32_e32 v75, v220, v75, vcc
	v_cmp_lt_u32_e32 vcc, s33, v148
	v_add_u32_e32 v148, 9, v197
	s_nop 0
	v_cndmask_b32_e32 v92, v220, v92, vcc
	v_cmp_lt_u32_e32 vcc, s33, v148
	v_add_u32_e32 v148, 40, v197
	s_nop 0
	v_cndmask_b32_e32 v76, v220, v76, vcc
	v_cmp_lt_u32_e32 vcc, s33, v148
	v_add_u32_e32 v148, 8, v197
	s_nop 0
	v_cndmask_b32_e32 v93, v220, v93, vcc
	v_cmp_lt_u32_e32 vcc, s33, v148
	v_add_u32_e32 v148, 35, v197
	s_nop 0
	v_cndmask_b32_e32 v77, v220, v77, vcc
	v_cmp_lt_u32_e32 vcc, s33, v148
	v_add_u32_e32 v148, 3, v197
	s_nop 0
	v_cndmask_b32_e32 v94, v220, v94, vcc
	v_cmp_lt_u32_e32 vcc, s33, v148
	v_add_u32_e32 v148, 34, v197
	s_nop 0
	v_cndmask_b32_e32 v78, v220, v78, vcc
	v_cmp_lt_u32_e32 vcc, s33, v148
	v_add_u32_e32 v148, 2, v197
	s_nop 0
	v_cndmask_b32_e32 v95, v220, v95, vcc
	v_cmp_lt_u32_e32 vcc, s33, v148
	v_add_u32_e32 v148, 33, v197
	s_nop 0
	v_cndmask_b32_e32 v79, v220, v79, vcc
	v_cmp_lt_u32_e32 vcc, s33, v148
	v_add_u32_e32 v148, 1, v197
	s_nop 0
	v_cndmask_b32_e32 v96, v220, v96, vcc
	v_cmp_lt_u32_e32 vcc, s33, v148
	v_add_u32_e32 v148, 32, v197
	s_nop 0
	v_cndmask_b32_e32 v80, v220, v80, vcc
	v_cmp_lt_u32_e32 vcc, s33, v148
	s_nop 1
	v_cndmask_b32_e32 v97, v220, v97, vcc
	v_cmp_lt_u32_e32 vcc, s33, v197
	s_nop 1
	v_cndmask_b32_e32 v81, v220, v81, vcc
